# K head-norm+rotary fused into the even in-proj epilogue of the K column block (no separate phase, one grid barrier fewer per even layer)
# speedup vs baseline: 1.0793x; 1.0145x over previous
; __global__ void __launch_bounds__(512, 2) fwd_kernel(Args a) {
;     ...
;     for (int ph = a.ph_lo; ph < a.ph_hi; ++ph) {
;         if (ph > 0 && ((ph - 1) & 3) == 1 && (((ph - 1) >> 2) & 1)) continue;
;     ...
;         const int kind = (ph == 0) ? 0 : ((((ph - 1) & 3) == 2) ? ((((ph - 1) >> 2) & 1) ? 3 : 2) : 1);
;         const int nrep = (kind == PROBE_KIND && a.ph_lo == 0) ? 2 : 1;
;     ...
;         const int nrep = 1;
;     ...
;         for (int rep = 0; rep < nrep; ++rep) {
;         const bool dry = (rep + 1 < nrep);
;         if (rep) { __syncthreads(); cg::this_grid().sync(); }
;         int tid = threadIdx.x; asm volatile("" : "+v"(tid));
;         const int lane = tid & 63;
;         if (ph == 0) {
;             if (DG(0)) prologue(a, lds, tid, lane, wid);
;             __syncthreads();
;         } else {
;             const int layer = (ph - 1) >> 2, sub4 = (ph - 1) & 3, j = layer >> 1; const bool even = (layer & 1) == 0;
;             const int sub = (sub4 == 0) ? 0 : (sub4 == 1 ? 3 : sub4 - 1);
;             if (sub == 3) {
;                 kprep_phase(P, a.in[7] + j * 64, rope, tid, bx, G);
.LBB0_9:
	s_cmp_lt_i32 s13, 1
	s_cselect_b64 s[16:17], -1, 0
	s_and_b32 s8, s13, 3
	s_cmp_lg_u32 s8, 2
	s_cselect_b64 s[22:23], -1, 0
	s_or_b64 s[16:17], s[16:17], s[22:23]
	s_and_b64 vcc, exec, s[16:17]
	s_mov_b64 s[38:39], -1
	s_cbranch_vccz .LBB0_530
	s_waitcnt vmcnt(0)
	v_sub_co_u32_e64 v0, s[16:17], s13, 1
	v_mov_b32_e32 v233, v199
	v_readfirstlane_b32 s37, v0
	s_andn2_b64 vcc, exec, s[16:17]
	v_and_b32_e32 v198, 63, v233
	v_writelane_b32 v255, s13, 49
	s_cbranch_vccz .LBB0_369
	s_and_b32 s8, s37, 3
	v_sub_co_u32_e64 v0, s[16:17], s8, 1
	s_cmp_lg_u32 s8, 1
	v_readfirstlane_b32 s8, v0
	s_cselect_b32 s8, s8, 3
	s_and_b64 s[16:17], s[16:17], exec
	s_cselect_b32 s45, 0, s8
	s_ashr_i32 s98, s37, 3
	s_bitcmp1_b32 s37, 2
	s_cselect_b64 s[8:9], -1, 0
	s_ashr_i32 s99, s98, 31
	v_writelane_b32 v255, s8, 50
	s_cmpk_lt_i32 s2, 0x300
	s_mov_b64 s[42:43], -1
	v_writelane_b32 v255, s9, 51
	s_cselect_b64 s[8:9], -1, 0
	v_writelane_b32 v255, s8, 52
	s_mov_b64 s[38:39], 0
	s_nop 0
	v_writelane_b32 v255, s9, 53
	s_ashr_i32 s8, s2, 31
	v_writelane_b32 v255, s8, 54
	s_lshr_b32 s8, s8, 29
	s_add_i32 s44, s2, s8
	s_and_b32 s8, s44, -8
	s_sub_i32 s28, s2, s8
	s_cmp_lt_i32 s28, 0
	s_cselect_b64 s[8:9], -1, 0
	v_writelane_b32 v255, s8, 55
	s_cmp_lt_i32 s45, 1
	s_nop 0
	v_writelane_b32 v255, s9, 56
	s_mov_b64 s[8:9], 0
	s_cbranch_scc1 .LBB0_142
	s_lshl_b32 s80, s98, 6
	s_ashr_i32 s81, s80, 31
	s_cmp_gt_i32 s45, 2
	s_mov_b64 s[38:39], -1
	s_cbranch_scc0 .LBB0_25
	v_lshl_add_u32 v26, s2, 9, v233
	s_mov_b32 s8, 0xc0000
	v_cmp_gt_i32_e32 vcc, s8, v26
	s_and_saveexec_b64 s[82:83], vcc
	v_readlane_b32 s22, v255, 19
	v_readlane_b32 s23, v255, 20
	s_cbranch_execz .LBB0_24
	v_cmp_lt_i32_e64 s[38:39], v222, v223
	s_lshl_b64 s[16:17], s[80:81], 2
	s_add_u32 s16, s62, s16
	v_cndmask_b32_e64 v1, v221, v222, s[38:39]
	v_cmp_lt_i32_e64 s[38:39], v224, v223
	v_lshlrev_b32_e32 v13, 2, v1
	v_and_b32_e32 v0, 7, v233
	v_cndmask_b32_e64 v1, v221, v224, s[38:39]
	v_cmp_lt_i32_e64 s[38:39], v225, v223
	v_lshlrev_b32_e32 v20, 2, v1
	s_addc_u32 s17, s63, s17
	v_cndmask_b32_e64 v1, v221, v225, s[38:39]
	v_cmp_gt_u32_e32 vcc, 4, v0
	v_lshlrev_b32_e32 v12, 3, v0
	v_lshlrev_b32_e32 v112, 5, v0
	v_mov_b32_e32 v0, 0
	v_lshlrev_b32_e32 v21, 2, v1
	v_lshlrev_b32_e32 v1, 3, v233
	v_lshl_add_u64 v[14:15], s[16:17], 0, v[112:113]
	v_lshl_add_u32 v22, s2, 12, v1
	s_mov_b64 s[84:85], 0
	v_mov_b32_e32 v1, v0
	v_mov_b32_e32 v2, v0
	v_mov_b32_e32 v3, v0
	v_mov_b32_e32 v4, v0
	v_mov_b32_e32 v5, v0
	v_mov_b32_e32 v6, v0
	v_mov_b32_e32 v7, v0
	s_branch .LBB0_16

; __device__ __forceinline__ u32x4 pack8(f32x4 a, f32x4 b) { u32x4 w; w.x = cvt_pk_bf16(a[0], a[1]); w.y = cvt_pk_bf16(a[2], a[3]); w.z = cvt_pk_bf16(b[0], b[1]); w.w = cvt_pk_bf16(b[2], b[3]); return w; }
;     __device__ __forceinline__ void operator()(const f32x4 (&acc)[2][2][4][2], const Unit& u, int wr, int wc, int fr_, int fq_, int slot) const {
;     ...
; #pragma unroll
;         for (int ai = 0; ai < 2; ++ai)
; #pragma unroll
;             for (int m = 0; m < 4; ++m) {
;                 bf16_t* rowp = P + (size_t)(u.pm * BM + ai * HALF + wr * 64 + m * 16 + fr) * EVEN_IN + col0;
; #pragma unroll
;                 for (int bj = 0; bj < 2; ++bj) {
;                     f32x4 v0 = acc[ai][bj][m][0] * rs[ai][m], v1 = acc[ai][bj][m][1] * rs[ai][m];
;                     *(u32x4*)(rowp + bj * HALF) = pack8(v0, v1);
;                 }
;                 asm volatile("" ::: "memory");
;             }
;     }
.LBB0_361:
	s_lshl_b32 s8, s91, 10
	s_and_b32 s8, s8, 0x400
	v_mov_b32_e32 v152, v160
	v_mov_b32_e32 v153, v159
	v_lshrrev_b32_e32 v200, 2, v159
	v_lshl_add_u32 v200, v160, 2, v200
	v_and_b32_e32 v201, 3, v159
	v_lshrrev_b32_e32 v202, 6, v233
	v_lshlrev_b32_e32 v202, 11, v202
	v_add_u32_e32 v202, 0x20000, v202
	v_mul_u32_u24_e32 v203, 0x50, v159
	v_lshl_add_u32 v203, v160, 4, v203
	v_add_u32_e32 v203, v203, v202
	v_mul_u32_u24_e32 v204, 0x50, v200
	v_lshl_add_u32 v204, v201, 4, v204
	v_add_u32_e32 v204, v204, v202
	s_add_i32 s8, s46, s8
	s_movk_i32 s13, 0x1200
	v_lshl_add_u32 v150, v153, 2, s8
	s_lshl_b32 s8, s22, 8
	s_or_b32 s8, s8, s35
	v_lshl_add_u32 v154, v201, 3, s8
	s_lshl_b32 s8, s90, 8
	s_add_i32 s8, s8, s33
	ds_read2_b32 v[164:165], v150 offset1:16
	ds_read2_b32 v[166:167], v150 offset0:32 offset1:48
	ds_read2_b32 v[156:157], v150 offset0:128 offset1:144
	ds_read2_b32 v[150:151], v150 offset0:160 offset1:176
	v_add_u32_e32 v172, s8, v200
	v_ashrrev_i32_e32 v155, 31, v154
	v_mov_b64_e32 v[152:153], s[0:1]
	v_mad_i64_i32 v[168:169], s[8:9], v172, s13, v[152:153]
	v_lshlrev_b64 v[154:155], 1, v[154:155]
	v_lshl_add_u64 v[168:169], v[168:169], 0, v[154:155]
	s_waitcnt lgkmcnt(0)
	v_pk_mul_f32 v[136:137], v[136:137], v[164:165] op_sel_hi:[1,0]
	v_pk_mul_f32 v[134:135], v[134:135], v[164:165] op_sel_hi:[1,0]
	v_pk_mul_f32 v[170:171], v[132:133], v[164:165] op_sel_hi:[1,0]
	v_pk_mul_f32 v[132:133], v[130:131], v[164:165] op_sel_hi:[1,0]
	v_cvt_pk_bf16_f32 v130, v134, v135
	v_cvt_pk_bf16_f32 v131, v136, v137
	v_pk_mul_f32 v[126:127], v[126:127], v[164:165] op_sel_hi:[1,0]
	v_cvt_pk_bf16_f32 v132, v132, v133
	v_cvt_pk_bf16_f32 v133, v170, v171
	ds_write_b128 v203, v[130:133]
	ds_read_b128 v[130:133], v204
	s_waitcnt lgkmcnt(0)
	global_store_dwordx4 v[168:169], v[130:133], off
	v_pk_mul_f32 v[128:129], v[128:129], v[164:165] op_sel_hi:[1,0]
	v_pk_mul_f32 v[104:105], v[104:105], v[166:167] op_sel_hi:[1,0]
	v_pk_mul_f32 v[130:131], v[120:121], v[164:165] op_sel_hi:[1,0]
	v_pk_mul_f32 v[120:121], v[118:119], v[164:165] op_sel_hi:[1,0]
	v_cvt_pk_bf16_f32 v118, v126, v127
	v_cvt_pk_bf16_f32 v119, v128, v129
	v_pk_mul_f32 v[92:93], v[92:93], v[166:167] op_sel_hi:[1,0]
	v_cvt_pk_bf16_f32 v120, v120, v121
	v_cvt_pk_bf16_f32 v121, v130, v131
	ds_write_b128 v203, v[118:121]
	ds_read_b128 v[118:121], v204
	s_waitcnt lgkmcnt(0)
	global_store_dwordx4 v[168:169], v[118:121], off offset:256
	v_pk_mul_f32 v[94:95], v[94:95], v[166:167] op_sel_hi:[1,0]
	v_pk_mul_f32 v[70:71], v[70:71], v[156:157] op_sel_hi:[1,0]
	v_add_u32_e32 v118, 16, v172
	v_mad_i64_i32 v[118:119], s[8:9], v118, s13, v[152:153]
	v_mov_b32_e32 v120, v165
	v_lshl_add_u64 v[118:119], v[118:119], 0, v[154:155]
	v_pk_mul_f32 v[124:125], v[124:125], v[120:121] op_sel_hi:[1,0]
	v_pk_mul_f32 v[122:123], v[122:123], v[120:121] op_sel_hi:[1,0]
	v_pk_mul_f32 v[126:127], v[116:117], v[120:121] op_sel_hi:[1,0]
	v_pk_mul_f32 v[116:117], v[114:115], v[120:121] op_sel_hi:[1,0]
	v_cvt_pk_bf16_f32 v114, v122, v123
	v_cvt_pk_bf16_f32 v115, v124, v125
	v_pk_mul_f32 v[108:109], v[108:109], v[120:121] op_sel_hi:[1,0]
	v_cvt_pk_bf16_f32 v116, v116, v117
	v_cvt_pk_bf16_f32 v117, v126, v127
	ds_write_b128 v203, v[114:117]
	ds_read_b128 v[114:117], v204
	s_waitcnt lgkmcnt(0)
	global_store_dwordx4 v[118:119], v[114:117], off
	v_pk_mul_f32 v[110:111], v[110:111], v[120:121] op_sel_hi:[1,0]
	v_pk_mul_f32 v[68:69], v[68:69], v[156:157] op_sel_hi:[1,0]
	v_pk_mul_f32 v[114:115], v[102:103], v[120:121] op_sel_hi:[1,0]
	v_pk_mul_f32 v[102:103], v[100:101], v[120:121] op_sel_hi:[1,0]
	v_cvt_pk_bf16_f32 v100, v108, v109
	v_cvt_pk_bf16_f32 v101, v110, v111
	v_pk_mul_f32 v[60:61], v[60:61], v[156:157] op_sel_hi:[1,0]
	v_cvt_pk_bf16_f32 v102, v102, v103
	v_cvt_pk_bf16_f32 v103, v114, v115
	ds_write_b128 v203, v[100:103]
	ds_read_b128 v[100:103], v204
	s_waitcnt lgkmcnt(0)
	global_store_dwordx4 v[118:119], v[100:103], off offset:256
	v_pk_mul_f32 v[62:63], v[62:63], v[156:157] op_sel_hi:[1,0]
	v_pk_mul_f32 v[40:41], v[40:41], v[150:151] op_sel_hi:[1,0]
	v_add_u32_e32 v100, 32, v172
	v_mad_i64_i32 v[100:101], s[8:9], v100, s13, v[152:153]
	v_lshl_add_u64 v[100:101], v[100:101], 0, v[154:155]
	v_pk_mul_f32 v[102:103], v[106:107], v[166:167] op_sel_hi:[1,0]
	v_pk_mul_f32 v[106:107], v[98:99], v[166:167] op_sel_hi:[1,0]
	v_pk_mul_f32 v[98:99], v[96:97], v[166:167] op_sel_hi:[1,0]
	v_cvt_pk_bf16_f32 v96, v104, v105
	v_cvt_pk_bf16_f32 v97, v102, v103
	v_pk_mul_f32 v[28:29], v[28:29], v[150:151] op_sel_hi:[1,0]
	v_cvt_pk_bf16_f32 v98, v98, v99
	v_cvt_pk_bf16_f32 v99, v106, v107
	ds_write_b128 v203, v[96:99]
	ds_read_b128 v[96:99], v204
	s_waitcnt lgkmcnt(0)
	global_store_dwordx4 v[100:101], v[96:99], off
	v_pk_mul_f32 v[30:31], v[30:31], v[150:151] op_sel_hi:[1,0]
	s_and_b64 vcc, exec, s[42:43]
	v_pk_mul_f32 v[96:97], v[86:87], v[166:167] op_sel_hi:[1,0]
	v_pk_mul_f32 v[86:87], v[84:85], v[166:167] op_sel_hi:[1,0]
	v_cvt_pk_bf16_f32 v84, v92, v93
	v_cvt_pk_bf16_f32 v85, v94, v95
	s_mov_b64 s[40:41], -1
	v_cvt_pk_bf16_f32 v86, v86, v87
	v_cvt_pk_bf16_f32 v87, v96, v97
	ds_write_b128 v203, v[84:87]
	ds_read_b128 v[84:87], v204
	s_waitcnt lgkmcnt(0)
	global_store_dwordx4 v[100:101], v[84:87], off offset:256
	s_nop 1
	v_add_u32_e32 v84, 48, v172
	v_mad_i64_i32 v[84:85], s[8:9], v84, s13, v[152:153]
	v_mov_b32_e32 v86, v167
	v_lshl_add_u64 v[84:85], v[84:85], 0, v[154:155]
	v_pk_mul_f32 v[90:91], v[90:91], v[86:87] op_sel_hi:[1,0]
	v_pk_mul_f32 v[88:89], v[88:89], v[86:87] op_sel_hi:[1,0]
	v_pk_mul_f32 v[92:93], v[82:83], v[86:87] op_sel_hi:[1,0]
	v_pk_mul_f32 v[82:83], v[80:81], v[86:87] op_sel_hi:[1,0]
	v_cvt_pk_bf16_f32 v80, v88, v89
	v_cvt_pk_bf16_f32 v81, v90, v91
	v_pk_mul_f32 v[76:77], v[76:77], v[86:87] op_sel_hi:[1,0]
	v_cvt_pk_bf16_f32 v82, v82, v83
	v_cvt_pk_bf16_f32 v83, v92, v93
	ds_write_b128 v203, v[80:83]
	ds_read_b128 v[80:83], v204
	s_waitcnt lgkmcnt(0)
; __device__ __forceinline__ u32x4 pack8(f32x4 a, f32x4 b) { u32x4 w; w.x = cvt_pk_bf16(a[0], a[1]); w.y = cvt_pk_bf16(a[2], a[3]); w.z = cvt_pk_bf16(b[0], b[1]); w.w = cvt_pk_bf16(b[2], b[3]); return w; }
;     __device__ __forceinline__ void operator()(const f32x4 (&acc)[2][2][4][2], const Unit& u, int wr, int wc, int fr_, int fq_, int slot) const {
;     ...
;         for (int ai = 0; ai < 2; ++ai)
; #pragma unroll
;             for (int m = 0; m < 4; ++m) {
;                 bf16_t* rowp = P + (size_t)(u.pm * BM + ai * HALF + wr * 64 + m * 16 + fr) * EVEN_IN + col0;
; #pragma unroll
;                 for (int bj = 0; bj < 2; ++bj) {
;                     f32x4 v0 = acc[ai][bj][m][0] * rs[ai][m], v1 = acc[ai][bj][m][1] * rs[ai][m];
;                     *(u32x4*)(rowp + bj * HALF) = pack8(v0, v1);
;                 }
;                 asm volatile("" ::: "memory");
;             }
;     }
	global_store_dwordx4 v[84:85], v[80:83], off
	v_pk_mul_f32 v[78:79], v[78:79], v[86:87] op_sel_hi:[1,0]
	s_nop 0
	v_pk_mul_f32 v[80:81], v[74:75], v[86:87] op_sel_hi:[1,0]
	v_pk_mul_f32 v[74:75], v[72:73], v[86:87] op_sel_hi:[1,0]
	v_cvt_pk_bf16_f32 v72, v76, v77
	v_cvt_pk_bf16_f32 v73, v78, v79
	s_nop 0
	v_cvt_pk_bf16_f32 v74, v74, v75
	v_cvt_pk_bf16_f32 v75, v80, v81
	ds_write_b128 v203, v[72:75]
	ds_read_b128 v[72:75], v204
	s_waitcnt lgkmcnt(0)
	global_store_dwordx4 v[84:85], v[72:75], off offset:256
	s_nop 1
	v_add_u32_e32 v72, 0x80, v172
	v_mad_i64_i32 v[72:73], s[8:9], v72, s13, v[152:153]
	v_lshl_add_u64 v[72:73], v[72:73], 0, v[154:155]
	v_pk_mul_f32 v[74:75], v[66:67], v[156:157] op_sel_hi:[1,0]
	v_pk_mul_f32 v[66:67], v[64:65], v[156:157] op_sel_hi:[1,0]
	v_cvt_pk_bf16_f32 v64, v68, v69
	v_cvt_pk_bf16_f32 v65, v70, v71
	s_nop 0
	v_cvt_pk_bf16_f32 v66, v66, v67
	v_cvt_pk_bf16_f32 v67, v74, v75
	ds_write_b128 v203, v[64:67]
	ds_read_b128 v[64:67], v204
	s_waitcnt lgkmcnt(0)
	global_store_dwordx4 v[72:73], v[64:67], off
	s_nop 1
	v_pk_mul_f32 v[64:65], v[54:55], v[156:157] op_sel_hi:[1,0]
	v_pk_mul_f32 v[54:55], v[52:53], v[156:157] op_sel_hi:[1,0]
	v_cvt_pk_bf16_f32 v52, v60, v61
	v_cvt_pk_bf16_f32 v53, v62, v63
	s_nop 0
	v_cvt_pk_bf16_f32 v54, v54, v55
	v_cvt_pk_bf16_f32 v55, v64, v65
	ds_write_b128 v203, v[52:55]
	ds_read_b128 v[52:55], v204
	s_waitcnt lgkmcnt(0)
	global_store_dwordx4 v[72:73], v[52:55], off offset:256
	s_nop 1
	v_add_u32_e32 v52, 0x90, v172
	v_mad_i64_i32 v[52:53], s[8:9], v52, s13, v[152:153]
	v_mov_b32_e32 v54, v157
	v_lshl_add_u64 v[52:53], v[52:53], 0, v[154:155]
	v_pk_mul_f32 v[58:59], v[58:59], v[54:55] op_sel_hi:[1,0]
	v_pk_mul_f32 v[56:57], v[56:57], v[54:55] op_sel_hi:[1,0]
	v_pk_mul_f32 v[60:61], v[50:51], v[54:55] op_sel_hi:[1,0]
	v_pk_mul_f32 v[50:51], v[48:49], v[54:55] op_sel_hi:[1,0]
	v_cvt_pk_bf16_f32 v48, v56, v57
	v_cvt_pk_bf16_f32 v49, v58, v59
	v_pk_mul_f32 v[44:45], v[44:45], v[54:55] op_sel_hi:[1,0]
	v_cvt_pk_bf16_f32 v50, v50, v51
	v_cvt_pk_bf16_f32 v51, v60, v61
	ds_write_b128 v203, v[48:51]
	ds_read_b128 v[48:51], v204
	s_waitcnt lgkmcnt(0)
	global_store_dwordx4 v[52:53], v[48:51], off
	v_pk_mul_f32 v[46:47], v[46:47], v[54:55] op_sel_hi:[1,0]
	s_nop 0
	v_pk_mul_f32 v[48:49], v[38:39], v[54:55] op_sel_hi:[1,0]
	v_pk_mul_f32 v[38:39], v[36:37], v[54:55] op_sel_hi:[1,0]
	v_cvt_pk_bf16_f32 v36, v44, v45
	v_cvt_pk_bf16_f32 v37, v46, v47
	s_nop 0
	v_cvt_pk_bf16_f32 v38, v38, v39
	v_cvt_pk_bf16_f32 v39, v48, v49
	ds_write_b128 v203, v[36:39]
	ds_read_b128 v[36:39], v204
	s_waitcnt lgkmcnt(0)
	global_store_dwordx4 v[52:53], v[36:39], off offset:256
	s_nop 1
	v_add_u32_e32 v36, 0xa0, v172
	v_mad_i64_i32 v[36:37], s[8:9], v36, s13, v[152:153]
	v_lshl_add_u64 v[36:37], v[36:37], 0, v[154:155]
	v_pk_mul_f32 v[38:39], v[42:43], v[150:151] op_sel_hi:[1,0]
	v_pk_mul_f32 v[42:43], v[34:35], v[150:151] op_sel_hi:[1,0]
	v_pk_mul_f32 v[34:35], v[32:33], v[150:151] op_sel_hi:[1,0]
	v_cvt_pk_bf16_f32 v32, v40, v41
	v_cvt_pk_bf16_f32 v33, v38, v39
	s_nop 0
	v_cvt_pk_bf16_f32 v34, v34, v35
	v_cvt_pk_bf16_f32 v35, v42, v43
	ds_write_b128 v203, v[32:35]
	ds_read_b128 v[32:35], v204
	s_waitcnt lgkmcnt(0)
	global_store_dwordx4 v[36:37], v[32:35], off
	s_nop 1
	v_pk_mul_f32 v[32:33], v[22:23], v[150:151] op_sel_hi:[1,0]
	v_pk_mul_f32 v[22:23], v[20:21], v[150:151] op_sel_hi:[1,0]
	v_cvt_pk_bf16_f32 v20, v28, v29
	v_cvt_pk_bf16_f32 v21, v30, v31
	s_nop 0
	v_cvt_pk_bf16_f32 v22, v22, v23
	v_cvt_pk_bf16_f32 v23, v32, v33
	ds_write_b128 v203, v[20:23]
	ds_read_b128 v[20:23], v204
	s_waitcnt lgkmcnt(0)
	global_store_dwordx4 v[36:37], v[20:23], off offset:256
	s_nop 1
	v_add_u32_e32 v20, 0xb0, v172
	v_mad_i64_i32 v[20:21], s[8:9], v20, s13, v[152:153]
	v_mov_b32_e32 v22, v151
	v_lshl_add_u64 v[20:21], v[20:21], 0, v[154:155]
	v_pk_mul_f32 v[26:27], v[26:27], v[22:23] op_sel_hi:[1,0]
	v_pk_mul_f32 v[24:25], v[24:25], v[22:23] op_sel_hi:[1,0]
	v_pk_mul_f32 v[28:29], v[18:19], v[22:23] op_sel_hi:[1,0]
	v_pk_mul_f32 v[18:19], v[16:17], v[22:23] op_sel_hi:[1,0]
	v_cvt_pk_bf16_f32 v16, v24, v25
	v_cvt_pk_bf16_f32 v17, v26, v27
	v_pk_mul_f32 v[14:15], v[14:15], v[22:23] op_sel_hi:[1,0]
	v_cvt_pk_bf16_f32 v18, v18, v19
	v_cvt_pk_bf16_f32 v19, v28, v29
	ds_write_b128 v203, v[16:19]
	ds_read_b128 v[16:19], v204
	s_waitcnt lgkmcnt(0)
	global_store_dwordx4 v[20:21], v[16:19], off
	v_pk_mul_f32 v[12:13], v[12:13], v[22:23] op_sel_hi:[1,0]
	v_readlane_b32 s13, v255, 49
	v_pk_mul_f32 v[16:17], v[10:11], v[22:23] op_sel_hi:[1,0]
	v_pk_mul_f32 v[10:11], v[8:9], v[22:23] op_sel_hi:[1,0]
	v_cvt_pk_bf16_f32 v8, v12, v13
	v_cvt_pk_bf16_f32 v9, v14, v15
	s_nop 0
	v_cvt_pk_bf16_f32 v10, v10, v11
	v_cvt_pk_bf16_f32 v11, v16, v17
	ds_write_b128 v203, v[8:11]
	ds_read_b128 v[8:11], v204
	s_waitcnt lgkmcnt(0)
	global_store_dwordx4 v[20:21], v[8:11], off offset:256
	s_cmp_lg_u32 s22, 6
	s_cbranch_scc1 .Lkp_skip
	s_waitcnt vmcnt(0)
	s_barrier
; __device__ __forceinline__ unsigned cvt_pk_bf16(float lo, float hi) { unsigned r; asm volatile("v_cvt_pk_bf16_f32 %0, %1, %2" : "=v"(r) : "v"(lo), "v"(hi)); return r; }
; __device__ __forceinline__ float bflo(unsigned w) { return __uint_as_float(w << 16); }
; __device__ __forceinline__ float bfhi(unsigned w) { return __uint_as_float(w & 0xffff0000u); }
; __device__ __forceinline__ void kprep_item(bf16_t* P, const float* kg, const float* rope, int idx, const u32x4 w) {
;     const int e8 = idx & 7, hk = (idx >> 3) & 1, row = idx >> 4;
;     float x[8] = {bflo(w.x), bfhi(w.x), bflo(w.y), bfhi(w.y), bflo(w.z), bfhi(w.z), bflo(w.w), bfhi(w.w)};
;     float ssq = 0.f;
; #pragma unroll
;     for (int e = 0; e < 8; ++e) ssq += x[e] * x[e];
;     ssq += __shfl_xor(ssq, 1); ssq += __shfl_xor(ssq, 2); ssq += __shfl_xor(ssq, 4);
;     const float rh = __builtin_amdgcn_rsqf(ssq * (1.0f / 64.0f) + EPS);
;     const int t = row & (SEQ - 1), ir = (e8 < 4) ? (t >> 6) : (t & 63), f0 = 8 * (e8 & 1);
;     const f32x4 g0 = *(const f32x4*)(kg + e8 * 8), g1 = *(const f32x4*)(kg + e8 * 8 + 4);
;     const f32x4 c0 = *(const f32x4*)(rope + ir * 16 + f0), c1 = *(const f32x4*)(rope + ir * 16 + f0 + 4);
;     const f32x4 s0 = *(const f32x4*)(rope + 1024 + ir * 16 + f0), s1 = *(const f32x4*)(rope + 1024 + ir * 16 + f0 + 4);
;     const float sgn = (e8 & 2) ? 1.0f : -1.0f;
;     float o[8];
; #pragma unroll
;     for (int e = 0; e < 8; ++e) {
;         const float y = x[e] * rh * (e < 4 ? g0[e & 3] : g1[e & 3]);
;         const float other = __shfl_xor(y, 2);
;         o[e] = y * (e < 4 ? c0[e & 3] : c1[e & 3]) + sgn * other * (e < 4 ? s0[e & 3] : s1[e & 3]);
;     }
;     u32x4 r; r.x = cvt_pk_bf16(o[0], o[1]); r.y = cvt_pk_bf16(o[2], o[3]); r.z = cvt_pk_bf16(o[4], o[5]); r.w = cvt_pk_bf16(o[6], o[7]);
;     *(u32x4*)(P + (size_t)row * EVEN_IN + 1536 + hk * 64 + e8 * 8) = r;
	v_and_b32_e32 v30, 7, v233
	v_bfe_u32 v31, v233, 3, 1
	v_lshrrev_b32_e32 v32, 4, v233
	s_lshl_b32 s8, s90, 8
	v_add_u32_e32 v32, s8, v32
	v_lshlrev_b32_e32 v33, 7, v31
	v_lshl_add_u32 v33, v30, 4, v33
	v_mul_u32_u24_e32 v36, 0x1200, v32
	v_add_u32_e32 v36, v36, v33
	v_mov_b32_e32 v37, v36
	global_load_dwordx4 v[48:51], v37, s[0:1] offset:3072 sc1
	v_add_u32_e32 v37, 0x24000, v37
	global_load_dwordx4 v[52:55], v37, s[0:1] offset:3072 sc1
	v_add_u32_e32 v37, 0x24000, v37
	global_load_dwordx4 v[56:59], v37, s[0:1] offset:3072 sc1
	v_add_u32_e32 v37, 0x24000, v37
	global_load_dwordx4 v[60:63], v37, s[0:1] offset:3072 sc1
	v_add_u32_e32 v37, 0x24000, v37
	global_load_dwordx4 v[64:67], v37, s[0:1] offset:3072 sc1
	v_add_u32_e32 v37, 0x24000, v37
	global_load_dwordx4 v[68:71], v37, s[0:1] offset:3072 sc1
	v_add_u32_e32 v37, 0x24000, v37
	global_load_dwordx4 v[72:75], v37, s[0:1] offset:3072 sc1
	v_add_u32_e32 v37, 0x24000, v37
	global_load_dwordx4 v[76:79], v37, s[0:1] offset:3072 sc1
	v_readlane_b32 s8, v255, 49
	s_nop 3
	s_add_i32 s8, s8, -1
	s_lshr_b32 s8, s8, 3
	s_lshl_b32 s8, s8, 8
	v_mov_b32_e32 v131, 0
	v_lshlrev_b32_e32 v130, 5, v30
	v_add_u32_e32 v130, s8, v130
	v_lshl_add_u64 v[244:245], s[62:63], 0, v[130:131]
	global_load_dwordx4 v[40:43], v[244:245], off
	global_load_dwordx4 v[44:47], v[244:245], off offset:16
	v_readlane_b32 s8, v253, 8
	v_readlane_b32 s9, v253, 9
	v_and_b32_e32 v38, 1, v30
	v_lshlrev_b32_e32 v38, 5, v38
	v_and_b32_e32 v39, 2, v30
	v_lshlrev_b32_e32 v39, 30, v39
	v_xor_b32_e32 v39, 0xbf800000, v39
	v_cmp_gt_u32_e32 vcc, 4, v30
	s_nop 3
	v_mov_b32_e32 v34, v32
	v_and_b32_e32 v35, 0xfff, v34
	v_lshrrev_b32_e32 v242, 6, v35
	v_and_b32_e32 v243, 63, v35
	v_cndmask_b32_e32 v242, v243, v242, vcc
	v_lshl_add_u32 v130, v242, 6, v38
	v_lshl_add_u64 v[244:245], s[8:9], 0, v[130:131]
	global_load_dwordx4 v[80:83], v[244:245], off
	global_load_dwordx4 v[84:87], v[244:245], off offset:16
	v_add_u32_e32 v130, 0x1000, v130
	v_lshl_add_u64 v[244:245], s[8:9], 0, v[130:131]
	global_load_dwordx4 v[88:91], v[244:245], off
	global_load_dwordx4 v[92:95], v[244:245], off offset:16
	v_add_u32_e32 v34, 32, v34
	v_and_b32_e32 v35, 0xfff, v34
	v_lshrrev_b32_e32 v242, 6, v35
	v_and_b32_e32 v243, 63, v35
	v_cndmask_b32_e32 v242, v243, v242, vcc
	v_lshl_add_u32 v130, v242, 6, v38
	v_lshl_add_u64 v[244:245], s[8:9], 0, v[130:131]
	global_load_dwordx4 v[96:99], v[244:245], off
	global_load_dwordx4 v[100:103], v[244:245], off offset:16
	v_add_u32_e32 v130, 0x1000, v130
	v_lshl_add_u64 v[244:245], s[8:9], 0, v[130:131]
	global_load_dwordx4 v[104:107], v[244:245], off
	global_load_dwordx4 v[108:111], v[244:245], off offset:16
	v_add_u32_e32 v34, 32, v34
	v_and_b32_e32 v35, 0xfff, v34
	v_lshrrev_b32_e32 v242, 6, v35
	v_and_b32_e32 v243, 63, v35
	v_cndmask_b32_e32 v242, v243, v242, vcc
	v_lshl_add_u32 v130, v242, 6, v38
	v_lshl_add_u64 v[244:245], s[8:9], 0, v[130:131]
	global_load_dwordx4 v[114:117], v[244:245], off
	global_load_dwordx4 v[118:121], v[244:245], off offset:16
	v_add_u32_e32 v130, 0x1000, v130
	v_lshl_add_u64 v[244:245], s[8:9], 0, v[130:131]
	global_load_dwordx4 v[122:125], v[244:245], off
	global_load_dwordx4 v[126:129], v[244:245], off offset:16
	s_waitcnt vmcnt(12)
	s_waitcnt vmcnt(8)
	v_lshlrev_b32_e32 v200, 16, v48
	v_and_b32_e32 v201, 0xffff0000, v48
	v_lshlrev_b32_e32 v202, 16, v49
	v_and_b32_e32 v203, 0xffff0000, v49
	v_lshlrev_b32_e32 v204, 16, v50
	v_and_b32_e32 v205, 0xffff0000, v50
	v_lshlrev_b32_e32 v206, 16, v51
	v_and_b32_e32 v207, 0xffff0000, v51
	v_mul_f32_e32 v234, v200, v200
	v_fmac_f32_e32 v234, v201, v201
	v_fmac_f32_e32 v234, v202, v202
	v_fmac_f32_e32 v234, v203, v203
	v_fmac_f32_e32 v234, v204, v204
	v_fmac_f32_e32 v234, v205, v205
	v_fmac_f32_e32 v234, v206, v206
	v_fmac_f32_e32 v234, v207, v207
	s_nop 1
	v_add_f32_dpp v235, v234, v234 quad_perm:[1,0,3,2] row_mask:0xf bank_mask:0xf
	s_nop 1
	v_add_f32_dpp v234, v235, v235 quad_perm:[2,3,0,1] row_mask:0xf bank_mask:0xf
	s_nop 1
	v_add_f32_dpp v235, v234, v234 row_half_mirror row_mask:0xf bank_mask:0xf
	v_fmamk_f32 v235, v235, 0x3c800000, v217
	v_rsq_f32_e32 v235, v235
	s_nop 0
	v_mul_f32_e32 v200, v200, v235
	v_mul_f32_e32 v201, v201, v235
	v_mul_f32_e32 v202, v202, v235
	v_mul_f32_e32 v203, v203, v235
	v_mul_f32_e32 v204, v204, v235
	v_mul_f32_e32 v205, v205, v235
	v_mul_f32_e32 v206, v206, v235
	v_mul_f32_e32 v207, v207, v235
	v_mul_f32_e32 v200, v200, v40
	v_mul_f32_e32 v201, v201, v41
	v_mul_f32_e32 v202, v202, v42
	v_mul_f32_e32 v203, v203, v43
	v_mul_f32_e32 v204, v204, v44
	v_mul_f32_e32 v205, v205, v45
	v_mul_f32_e32 v206, v206, v46
	v_mul_f32_e32 v207, v207, v47
	s_nop 1
	v_mov_b32_dpp v208, v200 quad_perm:[2,3,0,1] row_mask:0xf bank_mask:0xf
	v_mov_b32_dpp v209, v201 quad_perm:[2,3,0,1] row_mask:0xf bank_mask:0xf
	v_mov_b32_dpp v210, v202 quad_perm:[2,3,0,1] row_mask:0xf bank_mask:0xf
	v_mov_b32_dpp v211, v203 quad_perm:[2,3,0,1] row_mask:0xf bank_mask:0xf
	v_mov_b32_dpp v212, v204 quad_perm:[2,3,0,1] row_mask:0xf bank_mask:0xf
	v_mov_b32_dpp v213, v205 quad_perm:[2,3,0,1] row_mask:0xf bank_mask:0xf
	v_mov_b32_dpp v214, v206 quad_perm:[2,3,0,1] row_mask:0xf bank_mask:0xf
	v_mov_b32_dpp v215, v207 quad_perm:[2,3,0,1] row_mask:0xf bank_mask:0xf
	v_mul_f32_e32 v208, v39, v208
	v_mul_f32_e32 v209, v39, v209
	v_mul_f32_e32 v210, v39, v210
	v_mul_f32_e32 v211, v39, v211
	v_mul_f32_e32 v212, v39, v212
	v_mul_f32_e32 v213, v39, v213
	v_mul_f32_e32 v214, v39, v214
	v_mul_f32_e32 v215, v39, v215
	v_mul_f32_e32 v208, v208, v88
	v_mul_f32_e32 v209, v209, v89
	v_mul_f32_e32 v210, v210, v90
	v_mul_f32_e32 v211, v211, v91
	v_mul_f32_e32 v212, v212, v92
	v_mul_f32_e32 v213, v213, v93
	v_mul_f32_e32 v214, v214, v94
	v_mul_f32_e32 v215, v215, v95
	v_fma_f32 v200, v200, v80, v208
	v_fma_f32 v201, v201, v81, v209
	v_fma_f32 v202, v202, v82, v210
	v_fma_f32 v203, v203, v83, v211
	v_fma_f32 v204, v204, v84, v212
	v_fma_f32 v205, v205, v85, v213
	v_fma_f32 v206, v206, v86, v214
	v_fma_f32 v207, v207, v87, v215
	v_cvt_pk_bf16_f32 v240, v200, v201
	v_cvt_pk_bf16_f32 v241, v202, v203
	v_cvt_pk_bf16_f32 v242, v204, v205
	v_cvt_pk_bf16_f32 v243, v206, v207
	v_mov_b32_e32 v37, v36
	global_store_dwordx4 v37, v[240:243], s[0:1] offset:3072
	v_add_u32_e32 v34, 32, v34
	v_and_b32_e32 v35, 0xfff, v34
	v_lshrrev_b32_e32 v242, 6, v35
	v_and_b32_e32 v243, 63, v35
	v_cndmask_b32_e32 v242, v243, v242, vcc
	v_lshl_add_u32 v130, v242, 6, v38
	v_lshl_add_u64 v[244:245], s[8:9], 0, v[130:131]
	global_load_dwordx4 v[80:83], v[244:245], off
	global_load_dwordx4 v[84:87], v[244:245], off offset:16
	v_add_u32_e32 v130, 0x1000, v130
	v_lshl_add_u64 v[244:245], s[8:9], 0, v[130:131]
	global_load_dwordx4 v[88:91], v[244:245], off
	global_load_dwordx4 v[92:95], v[244:245], off offset:16
	s_waitcnt vmcnt(9)
; __device__ __forceinline__ unsigned cvt_pk_bf16(float lo, float hi) { unsigned r; asm volatile("v_cvt_pk_bf16_f32 %0, %1, %2" : "=v"(r) : "v"(lo), "v"(hi)); return r; }
; __device__ __forceinline__ float bflo(unsigned w) { return __uint_as_float(w << 16); }
; __device__ __forceinline__ float bfhi(unsigned w) { return __uint_as_float(w & 0xffff0000u); }
; __device__ __forceinline__ void kprep_item(bf16_t* P, const float* kg, const float* rope, int idx, const u32x4 w) {
;     const int e8 = idx & 7, hk = (idx >> 3) & 1, row = idx >> 4;
;     float x[8] = {bflo(w.x), bfhi(w.x), bflo(w.y), bfhi(w.y), bflo(w.z), bfhi(w.z), bflo(w.w), bfhi(w.w)};
;     float ssq = 0.f;
; #pragma unroll
;     for (int e = 0; e < 8; ++e) ssq += x[e] * x[e];
;     ssq += __shfl_xor(ssq, 1); ssq += __shfl_xor(ssq, 2); ssq += __shfl_xor(ssq, 4);
;     const float rh = __builtin_amdgcn_rsqf(ssq * (1.0f / 64.0f) + EPS);
;     const int t = row & (SEQ - 1), ir = (e8 < 4) ? (t >> 6) : (t & 63), f0 = 8 * (e8 & 1);
;     const f32x4 g0 = *(const f32x4*)(kg + e8 * 8), g1 = *(const f32x4*)(kg + e8 * 8 + 4);
;     const f32x4 c0 = *(const f32x4*)(rope + ir * 16 + f0), c1 = *(const f32x4*)(rope + ir * 16 + f0 + 4);
;     const f32x4 s0 = *(const f32x4*)(rope + 1024 + ir * 16 + f0), s1 = *(const f32x4*)(rope + 1024 + ir * 16 + f0 + 4);
;     const float sgn = (e8 & 2) ? 1.0f : -1.0f;
;     float o[8];
; #pragma unroll
;     for (int e = 0; e < 8; ++e) {
;         const float y = x[e] * rh * (e < 4 ? g0[e & 3] : g1[e & 3]);
;         const float other = __shfl_xor(y, 2);
;         o[e] = y * (e < 4 ? c0[e & 3] : c1[e & 3]) + sgn * other * (e < 4 ? s0[e & 3] : s1[e & 3]);
;     }
;     u32x4 r; r.x = cvt_pk_bf16(o[0], o[1]); r.y = cvt_pk_bf16(o[2], o[3]); r.z = cvt_pk_bf16(o[4], o[5]); r.w = cvt_pk_bf16(o[6], o[7]);
;     *(u32x4*)(P + (size_t)row * EVEN_IN + 1536 + hk * 64 + e8 * 8) = r;
	v_lshlrev_b32_e32 v200, 16, v52
	v_and_b32_e32 v201, 0xffff0000, v52
	v_lshlrev_b32_e32 v202, 16, v53
	v_and_b32_e32 v203, 0xffff0000, v53
	v_lshlrev_b32_e32 v204, 16, v54
	v_and_b32_e32 v205, 0xffff0000, v54
	v_lshlrev_b32_e32 v206, 16, v55
	v_and_b32_e32 v207, 0xffff0000, v55
	v_mul_f32_e32 v234, v200, v200
	v_fmac_f32_e32 v234, v201, v201
	v_fmac_f32_e32 v234, v202, v202
	v_fmac_f32_e32 v234, v203, v203
	v_fmac_f32_e32 v234, v204, v204
	v_fmac_f32_e32 v234, v205, v205
	v_fmac_f32_e32 v234, v206, v206
	v_fmac_f32_e32 v234, v207, v207
	s_nop 1
	v_add_f32_dpp v235, v234, v234 quad_perm:[1,0,3,2] row_mask:0xf bank_mask:0xf
	s_nop 1
	v_add_f32_dpp v234, v235, v235 quad_perm:[2,3,0,1] row_mask:0xf bank_mask:0xf
	s_nop 1
	v_add_f32_dpp v235, v234, v234 row_half_mirror row_mask:0xf bank_mask:0xf
	v_fmamk_f32 v235, v235, 0x3c800000, v217
	v_rsq_f32_e32 v235, v235
	s_nop 0
	v_mul_f32_e32 v200, v200, v235
	v_mul_f32_e32 v201, v201, v235
	v_mul_f32_e32 v202, v202, v235
	v_mul_f32_e32 v203, v203, v235
	v_mul_f32_e32 v204, v204, v235
	v_mul_f32_e32 v205, v205, v235
	v_mul_f32_e32 v206, v206, v235
	v_mul_f32_e32 v207, v207, v235
	v_mul_f32_e32 v200, v200, v40
	v_mul_f32_e32 v201, v201, v41
	v_mul_f32_e32 v202, v202, v42
	v_mul_f32_e32 v203, v203, v43
	v_mul_f32_e32 v204, v204, v44
	v_mul_f32_e32 v205, v205, v45
	v_mul_f32_e32 v206, v206, v46
	v_mul_f32_e32 v207, v207, v47
	s_nop 1
	v_mov_b32_dpp v208, v200 quad_perm:[2,3,0,1] row_mask:0xf bank_mask:0xf
	v_mov_b32_dpp v209, v201 quad_perm:[2,3,0,1] row_mask:0xf bank_mask:0xf
	v_mov_b32_dpp v210, v202 quad_perm:[2,3,0,1] row_mask:0xf bank_mask:0xf
	v_mov_b32_dpp v211, v203 quad_perm:[2,3,0,1] row_mask:0xf bank_mask:0xf
	v_mov_b32_dpp v212, v204 quad_perm:[2,3,0,1] row_mask:0xf bank_mask:0xf
	v_mov_b32_dpp v213, v205 quad_perm:[2,3,0,1] row_mask:0xf bank_mask:0xf
	v_mov_b32_dpp v214, v206 quad_perm:[2,3,0,1] row_mask:0xf bank_mask:0xf
	v_mov_b32_dpp v215, v207 quad_perm:[2,3,0,1] row_mask:0xf bank_mask:0xf
	v_mul_f32_e32 v208, v39, v208
	v_mul_f32_e32 v209, v39, v209
	v_mul_f32_e32 v210, v39, v210
	v_mul_f32_e32 v211, v39, v211
	v_mul_f32_e32 v212, v39, v212
	v_mul_f32_e32 v213, v39, v213
	v_mul_f32_e32 v214, v39, v214
	v_mul_f32_e32 v215, v39, v215
	v_mul_f32_e32 v208, v208, v104
	v_mul_f32_e32 v209, v209, v105
	v_mul_f32_e32 v210, v210, v106
	v_mul_f32_e32 v211, v211, v107
	v_mul_f32_e32 v212, v212, v108
	v_mul_f32_e32 v213, v213, v109
	v_mul_f32_e32 v214, v214, v110
	v_mul_f32_e32 v215, v215, v111
	v_fma_f32 v200, v200, v96, v208
	v_fma_f32 v201, v201, v97, v209
	v_fma_f32 v202, v202, v98, v210
	v_fma_f32 v203, v203, v99, v211
	v_fma_f32 v204, v204, v100, v212
	v_fma_f32 v205, v205, v101, v213
	v_fma_f32 v206, v206, v102, v214
	v_fma_f32 v207, v207, v103, v215
	v_cvt_pk_bf16_f32 v240, v200, v201
	v_cvt_pk_bf16_f32 v241, v202, v203
	v_cvt_pk_bf16_f32 v242, v204, v205
	v_cvt_pk_bf16_f32 v243, v206, v207
	v_add_u32_e32 v37, 0x24000, v37
	global_store_dwordx4 v37, v[240:243], s[0:1] offset:3072
	v_add_u32_e32 v34, 32, v34
	v_and_b32_e32 v35, 0xfff, v34
	v_lshrrev_b32_e32 v242, 6, v35
	v_and_b32_e32 v243, 63, v35
	v_cndmask_b32_e32 v242, v243, v242, vcc
	v_lshl_add_u32 v130, v242, 6, v38
	v_lshl_add_u64 v[244:245], s[8:9], 0, v[130:131]
	global_load_dwordx4 v[96:99], v[244:245], off
	global_load_dwordx4 v[100:103], v[244:245], off offset:16
	v_add_u32_e32 v130, 0x1000, v130
	v_lshl_add_u64 v[244:245], s[8:9], 0, v[130:131]
	global_load_dwordx4 v[104:107], v[244:245], off
	global_load_dwordx4 v[108:111], v[244:245], off offset:16
	s_waitcnt vmcnt(10)
	v_lshlrev_b32_e32 v200, 16, v56
	v_and_b32_e32 v201, 0xffff0000, v56
	v_lshlrev_b32_e32 v202, 16, v57
	v_and_b32_e32 v203, 0xffff0000, v57
	v_lshlrev_b32_e32 v204, 16, v58
	v_and_b32_e32 v205, 0xffff0000, v58
	v_lshlrev_b32_e32 v206, 16, v59
	v_and_b32_e32 v207, 0xffff0000, v59
	v_mul_f32_e32 v234, v200, v200
	v_fmac_f32_e32 v234, v201, v201
	v_fmac_f32_e32 v234, v202, v202
	v_fmac_f32_e32 v234, v203, v203
	v_fmac_f32_e32 v234, v204, v204
	v_fmac_f32_e32 v234, v205, v205
	v_fmac_f32_e32 v234, v206, v206
	v_fmac_f32_e32 v234, v207, v207
	s_nop 1
	v_add_f32_dpp v235, v234, v234 quad_perm:[1,0,3,2] row_mask:0xf bank_mask:0xf
	s_nop 1
	v_add_f32_dpp v234, v235, v235 quad_perm:[2,3,0,1] row_mask:0xf bank_mask:0xf
	s_nop 1
	v_add_f32_dpp v235, v234, v234 row_half_mirror row_mask:0xf bank_mask:0xf
	v_fmamk_f32 v235, v235, 0x3c800000, v217
	v_rsq_f32_e32 v235, v235
	s_nop 0
	v_mul_f32_e32 v200, v200, v235
	v_mul_f32_e32 v201, v201, v235
	v_mul_f32_e32 v202, v202, v235
	v_mul_f32_e32 v203, v203, v235
	v_mul_f32_e32 v204, v204, v235
	v_mul_f32_e32 v205, v205, v235
	v_mul_f32_e32 v206, v206, v235
	v_mul_f32_e32 v207, v207, v235
	v_mul_f32_e32 v200, v200, v40
	v_mul_f32_e32 v201, v201, v41
	v_mul_f32_e32 v202, v202, v42
	v_mul_f32_e32 v203, v203, v43
	v_mul_f32_e32 v204, v204, v44
	v_mul_f32_e32 v205, v205, v45
	v_mul_f32_e32 v206, v206, v46
	v_mul_f32_e32 v207, v207, v47
	s_nop 1
	v_mov_b32_dpp v208, v200 quad_perm:[2,3,0,1] row_mask:0xf bank_mask:0xf
	v_mov_b32_dpp v209, v201 quad_perm:[2,3,0,1] row_mask:0xf bank_mask:0xf
	v_mov_b32_dpp v210, v202 quad_perm:[2,3,0,1] row_mask:0xf bank_mask:0xf
	v_mov_b32_dpp v211, v203 quad_perm:[2,3,0,1] row_mask:0xf bank_mask:0xf
	v_mov_b32_dpp v212, v204 quad_perm:[2,3,0,1] row_mask:0xf bank_mask:0xf
	v_mov_b32_dpp v213, v205 quad_perm:[2,3,0,1] row_mask:0xf bank_mask:0xf
	v_mov_b32_dpp v214, v206 quad_perm:[2,3,0,1] row_mask:0xf bank_mask:0xf
	v_mov_b32_dpp v215, v207 quad_perm:[2,3,0,1] row_mask:0xf bank_mask:0xf
	v_mul_f32_e32 v208, v39, v208
	v_mul_f32_e32 v209, v39, v209
	v_mul_f32_e32 v210, v39, v210
	v_mul_f32_e32 v211, v39, v211
; __device__ __forceinline__ unsigned cvt_pk_bf16(float lo, float hi) { unsigned r; asm volatile("v_cvt_pk_bf16_f32 %0, %1, %2" : "=v"(r) : "v"(lo), "v"(hi)); return r; }
; __device__ __forceinline__ float bflo(unsigned w) { return __uint_as_float(w << 16); }
; __device__ __forceinline__ float bfhi(unsigned w) { return __uint_as_float(w & 0xffff0000u); }
; __device__ __forceinline__ void kprep_item(bf16_t* P, const float* kg, const float* rope, int idx, const u32x4 w) {
;     const int e8 = idx & 7, hk = (idx >> 3) & 1, row = idx >> 4;
;     float x[8] = {bflo(w.x), bfhi(w.x), bflo(w.y), bfhi(w.y), bflo(w.z), bfhi(w.z), bflo(w.w), bfhi(w.w)};
;     float ssq = 0.f;
; #pragma unroll
;     for (int e = 0; e < 8; ++e) ssq += x[e] * x[e];
;     ssq += __shfl_xor(ssq, 1); ssq += __shfl_xor(ssq, 2); ssq += __shfl_xor(ssq, 4);
;     const float rh = __builtin_amdgcn_rsqf(ssq * (1.0f / 64.0f) + EPS);
;     const int t = row & (SEQ - 1), ir = (e8 < 4) ? (t >> 6) : (t & 63), f0 = 8 * (e8 & 1);
;     const f32x4 g0 = *(const f32x4*)(kg + e8 * 8), g1 = *(const f32x4*)(kg + e8 * 8 + 4);
;     const f32x4 c0 = *(const f32x4*)(rope + ir * 16 + f0), c1 = *(const f32x4*)(rope + ir * 16 + f0 + 4);
;     const f32x4 s0 = *(const f32x4*)(rope + 1024 + ir * 16 + f0), s1 = *(const f32x4*)(rope + 1024 + ir * 16 + f0 + 4);
;     const float sgn = (e8 & 2) ? 1.0f : -1.0f;
;     float o[8];
; #pragma unroll
;     for (int e = 0; e < 8; ++e) {
;         const float y = x[e] * rh * (e < 4 ? g0[e & 3] : g1[e & 3]);
;         const float other = __shfl_xor(y, 2);
;         o[e] = y * (e < 4 ? c0[e & 3] : c1[e & 3]) + sgn * other * (e < 4 ? s0[e & 3] : s1[e & 3]);
;     }
;     u32x4 r; r.x = cvt_pk_bf16(o[0], o[1]); r.y = cvt_pk_bf16(o[2], o[3]); r.z = cvt_pk_bf16(o[4], o[5]); r.w = cvt_pk_bf16(o[6], o[7]);
;     *(u32x4*)(P + (size_t)row * EVEN_IN + 1536 + hk * 64 + e8 * 8) = r;
	v_mul_f32_e32 v212, v39, v212
	v_mul_f32_e32 v213, v39, v213
	v_mul_f32_e32 v214, v39, v214
	v_mul_f32_e32 v215, v39, v215
	v_mul_f32_e32 v208, v208, v122
	v_mul_f32_e32 v209, v209, v123
	v_mul_f32_e32 v210, v210, v124
	v_mul_f32_e32 v211, v211, v125
	v_mul_f32_e32 v212, v212, v126
	v_mul_f32_e32 v213, v213, v127
	v_mul_f32_e32 v214, v214, v128
	v_mul_f32_e32 v215, v215, v129
	v_fma_f32 v200, v200, v114, v208
	v_fma_f32 v201, v201, v115, v209
	v_fma_f32 v202, v202, v116, v210
	v_fma_f32 v203, v203, v117, v211
	v_fma_f32 v204, v204, v118, v212
	v_fma_f32 v205, v205, v119, v213
	v_fma_f32 v206, v206, v120, v214
	v_fma_f32 v207, v207, v121, v215
	v_cvt_pk_bf16_f32 v240, v200, v201
	v_cvt_pk_bf16_f32 v241, v202, v203
	v_cvt_pk_bf16_f32 v242, v204, v205
	v_cvt_pk_bf16_f32 v243, v206, v207
	v_add_u32_e32 v37, 0x24000, v37
	global_store_dwordx4 v37, v[240:243], s[0:1] offset:3072
	v_add_u32_e32 v34, 32, v34
	v_and_b32_e32 v35, 0xfff, v34
	v_lshrrev_b32_e32 v242, 6, v35
	v_and_b32_e32 v243, 63, v35
	v_cndmask_b32_e32 v242, v243, v242, vcc
	v_lshl_add_u32 v130, v242, 6, v38
	v_lshl_add_u64 v[244:245], s[8:9], 0, v[130:131]
	global_load_dwordx4 v[114:117], v[244:245], off
	global_load_dwordx4 v[118:121], v[244:245], off offset:16
	v_add_u32_e32 v130, 0x1000, v130
	v_lshl_add_u64 v[244:245], s[8:9], 0, v[130:131]
	global_load_dwordx4 v[122:125], v[244:245], off
	global_load_dwordx4 v[126:129], v[244:245], off offset:16
	s_waitcnt vmcnt(10)
	v_lshlrev_b32_e32 v200, 16, v60
	v_and_b32_e32 v201, 0xffff0000, v60
	v_lshlrev_b32_e32 v202, 16, v61
	v_and_b32_e32 v203, 0xffff0000, v61
	v_lshlrev_b32_e32 v204, 16, v62
	v_and_b32_e32 v205, 0xffff0000, v62
	v_lshlrev_b32_e32 v206, 16, v63
	v_and_b32_e32 v207, 0xffff0000, v63
	v_mul_f32_e32 v234, v200, v200
	v_fmac_f32_e32 v234, v201, v201
	v_fmac_f32_e32 v234, v202, v202
	v_fmac_f32_e32 v234, v203, v203
	v_fmac_f32_e32 v234, v204, v204
	v_fmac_f32_e32 v234, v205, v205
	v_fmac_f32_e32 v234, v206, v206
	v_fmac_f32_e32 v234, v207, v207
	s_nop 1
	v_add_f32_dpp v235, v234, v234 quad_perm:[1,0,3,2] row_mask:0xf bank_mask:0xf
	s_nop 1
	v_add_f32_dpp v234, v235, v235 quad_perm:[2,3,0,1] row_mask:0xf bank_mask:0xf
	s_nop 1
	v_add_f32_dpp v235, v234, v234 row_half_mirror row_mask:0xf bank_mask:0xf
	v_fmamk_f32 v235, v235, 0x3c800000, v217
	v_rsq_f32_e32 v235, v235
	s_nop 0
	v_mul_f32_e32 v200, v200, v235
	v_mul_f32_e32 v201, v201, v235
	v_mul_f32_e32 v202, v202, v235
	v_mul_f32_e32 v203, v203, v235
	v_mul_f32_e32 v204, v204, v235
	v_mul_f32_e32 v205, v205, v235
	v_mul_f32_e32 v206, v206, v235
	v_mul_f32_e32 v207, v207, v235
	v_mul_f32_e32 v200, v200, v40
	v_mul_f32_e32 v201, v201, v41
	v_mul_f32_e32 v202, v202, v42
	v_mul_f32_e32 v203, v203, v43
	v_mul_f32_e32 v204, v204, v44
	v_mul_f32_e32 v205, v205, v45
	v_mul_f32_e32 v206, v206, v46
	v_mul_f32_e32 v207, v207, v47
	s_nop 1
	v_mov_b32_dpp v208, v200 quad_perm:[2,3,0,1] row_mask:0xf bank_mask:0xf
	v_mov_b32_dpp v209, v201 quad_perm:[2,3,0,1] row_mask:0xf bank_mask:0xf
	v_mov_b32_dpp v210, v202 quad_perm:[2,3,0,1] row_mask:0xf bank_mask:0xf
	v_mov_b32_dpp v211, v203 quad_perm:[2,3,0,1] row_mask:0xf bank_mask:0xf
	v_mov_b32_dpp v212, v204 quad_perm:[2,3,0,1] row_mask:0xf bank_mask:0xf
	v_mov_b32_dpp v213, v205 quad_perm:[2,3,0,1] row_mask:0xf bank_mask:0xf
	v_mov_b32_dpp v214, v206 quad_perm:[2,3,0,1] row_mask:0xf bank_mask:0xf
	v_mov_b32_dpp v215, v207 quad_perm:[2,3,0,1] row_mask:0xf bank_mask:0xf
	v_mul_f32_e32 v208, v39, v208
	v_mul_f32_e32 v209, v39, v209
	v_mul_f32_e32 v210, v39, v210
	v_mul_f32_e32 v211, v39, v211
	v_mul_f32_e32 v212, v39, v212
	v_mul_f32_e32 v213, v39, v213
	v_mul_f32_e32 v214, v39, v214
	v_mul_f32_e32 v215, v39, v215
	v_mul_f32_e32 v208, v208, v88
	v_mul_f32_e32 v209, v209, v89
	v_mul_f32_e32 v210, v210, v90
	v_mul_f32_e32 v211, v211, v91
	v_mul_f32_e32 v212, v212, v92
	v_mul_f32_e32 v213, v213, v93
	v_mul_f32_e32 v214, v214, v94
	v_mul_f32_e32 v215, v215, v95
	v_fma_f32 v200, v200, v80, v208
	v_fma_f32 v201, v201, v81, v209
	v_fma_f32 v202, v202, v82, v210
	v_fma_f32 v203, v203, v83, v211
	v_fma_f32 v204, v204, v84, v212
	v_fma_f32 v205, v205, v85, v213
	v_fma_f32 v206, v206, v86, v214
	v_fma_f32 v207, v207, v87, v215
	v_cvt_pk_bf16_f32 v240, v200, v201
	v_cvt_pk_bf16_f32 v241, v202, v203
	v_cvt_pk_bf16_f32 v242, v204, v205
	v_cvt_pk_bf16_f32 v243, v206, v207
	v_add_u32_e32 v37, 0x24000, v37
	global_store_dwordx4 v37, v[240:243], s[0:1] offset:3072
	v_add_u32_e32 v34, 32, v34
	v_and_b32_e32 v35, 0xfff, v34
	v_lshrrev_b32_e32 v242, 6, v35
	v_and_b32_e32 v243, 63, v35
	v_cndmask_b32_e32 v242, v243, v242, vcc
	v_lshl_add_u32 v130, v242, 6, v38
	v_lshl_add_u64 v[244:245], s[8:9], 0, v[130:131]
	global_load_dwordx4 v[80:83], v[244:245], off
	global_load_dwordx4 v[84:87], v[244:245], off offset:16
	v_add_u32_e32 v130, 0x1000, v130
	v_lshl_add_u64 v[244:245], s[8:9], 0, v[130:131]
	global_load_dwordx4 v[88:91], v[244:245], off
	global_load_dwordx4 v[92:95], v[244:245], off offset:16
	s_waitcnt vmcnt(10)
; __device__ __forceinline__ unsigned cvt_pk_bf16(float lo, float hi) { unsigned r; asm volatile("v_cvt_pk_bf16_f32 %0, %1, %2" : "=v"(r) : "v"(lo), "v"(hi)); return r; }
; __device__ __forceinline__ float bflo(unsigned w) { return __uint_as_float(w << 16); }
; __device__ __forceinline__ float bfhi(unsigned w) { return __uint_as_float(w & 0xffff0000u); }
; __device__ __forceinline__ void kprep_item(bf16_t* P, const float* kg, const float* rope, int idx, const u32x4 w) {
;     const int e8 = idx & 7, hk = (idx >> 3) & 1, row = idx >> 4;
;     float x[8] = {bflo(w.x), bfhi(w.x), bflo(w.y), bfhi(w.y), bflo(w.z), bfhi(w.z), bflo(w.w), bfhi(w.w)};
;     float ssq = 0.f;
; #pragma unroll
;     for (int e = 0; e < 8; ++e) ssq += x[e] * x[e];
;     ssq += __shfl_xor(ssq, 1); ssq += __shfl_xor(ssq, 2); ssq += __shfl_xor(ssq, 4);
;     const float rh = __builtin_amdgcn_rsqf(ssq * (1.0f / 64.0f) + EPS);
;     const int t = row & (SEQ - 1), ir = (e8 < 4) ? (t >> 6) : (t & 63), f0 = 8 * (e8 & 1);
;     const f32x4 g0 = *(const f32x4*)(kg + e8 * 8), g1 = *(const f32x4*)(kg + e8 * 8 + 4);
;     const f32x4 c0 = *(const f32x4*)(rope + ir * 16 + f0), c1 = *(const f32x4*)(rope + ir * 16 + f0 + 4);
;     const f32x4 s0 = *(const f32x4*)(rope + 1024 + ir * 16 + f0), s1 = *(const f32x4*)(rope + 1024 + ir * 16 + f0 + 4);
;     const float sgn = (e8 & 2) ? 1.0f : -1.0f;
;     float o[8];
; #pragma unroll
;     for (int e = 0; e < 8; ++e) {
;         const float y = x[e] * rh * (e < 4 ? g0[e & 3] : g1[e & 3]);
;         const float other = __shfl_xor(y, 2);
;         o[e] = y * (e < 4 ? c0[e & 3] : c1[e & 3]) + sgn * other * (e < 4 ? s0[e & 3] : s1[e & 3]);
;     }
;     u32x4 r; r.x = cvt_pk_bf16(o[0], o[1]); r.y = cvt_pk_bf16(o[2], o[3]); r.z = cvt_pk_bf16(o[4], o[5]); r.w = cvt_pk_bf16(o[6], o[7]);
;     *(u32x4*)(P + (size_t)row * EVEN_IN + 1536 + hk * 64 + e8 * 8) = r;
	v_lshlrev_b32_e32 v200, 16, v64
	v_and_b32_e32 v201, 0xffff0000, v64
	v_lshlrev_b32_e32 v202, 16, v65
	v_and_b32_e32 v203, 0xffff0000, v65
	v_lshlrev_b32_e32 v204, 16, v66
	v_and_b32_e32 v205, 0xffff0000, v66
	v_lshlrev_b32_e32 v206, 16, v67
	v_and_b32_e32 v207, 0xffff0000, v67
	v_mul_f32_e32 v234, v200, v200
	v_fmac_f32_e32 v234, v201, v201
	v_fmac_f32_e32 v234, v202, v202
	v_fmac_f32_e32 v234, v203, v203
	v_fmac_f32_e32 v234, v204, v204
	v_fmac_f32_e32 v234, v205, v205
	v_fmac_f32_e32 v234, v206, v206
	v_fmac_f32_e32 v234, v207, v207
	s_nop 1
	v_add_f32_dpp v235, v234, v234 quad_perm:[1,0,3,2] row_mask:0xf bank_mask:0xf
	s_nop 1
	v_add_f32_dpp v234, v235, v235 quad_perm:[2,3,0,1] row_mask:0xf bank_mask:0xf
	s_nop 1
	v_add_f32_dpp v235, v234, v234 row_half_mirror row_mask:0xf bank_mask:0xf
	v_fmamk_f32 v235, v235, 0x3c800000, v217
	v_rsq_f32_e32 v235, v235
	s_nop 0
	v_mul_f32_e32 v200, v200, v235
	v_mul_f32_e32 v201, v201, v235
	v_mul_f32_e32 v202, v202, v235
	v_mul_f32_e32 v203, v203, v235
	v_mul_f32_e32 v204, v204, v235
	v_mul_f32_e32 v205, v205, v235
	v_mul_f32_e32 v206, v206, v235
	v_mul_f32_e32 v207, v207, v235
	v_mul_f32_e32 v200, v200, v40
	v_mul_f32_e32 v201, v201, v41
	v_mul_f32_e32 v202, v202, v42
	v_mul_f32_e32 v203, v203, v43
	v_mul_f32_e32 v204, v204, v44
	v_mul_f32_e32 v205, v205, v45
	v_mul_f32_e32 v206, v206, v46
	v_mul_f32_e32 v207, v207, v47
	s_nop 1
	v_mov_b32_dpp v208, v200 quad_perm:[2,3,0,1] row_mask:0xf bank_mask:0xf
	v_mov_b32_dpp v209, v201 quad_perm:[2,3,0,1] row_mask:0xf bank_mask:0xf
	v_mov_b32_dpp v210, v202 quad_perm:[2,3,0,1] row_mask:0xf bank_mask:0xf
	v_mov_b32_dpp v211, v203 quad_perm:[2,3,0,1] row_mask:0xf bank_mask:0xf
	v_mov_b32_dpp v212, v204 quad_perm:[2,3,0,1] row_mask:0xf bank_mask:0xf
	v_mov_b32_dpp v213, v205 quad_perm:[2,3,0,1] row_mask:0xf bank_mask:0xf
	v_mov_b32_dpp v214, v206 quad_perm:[2,3,0,1] row_mask:0xf bank_mask:0xf
	v_mov_b32_dpp v215, v207 quad_perm:[2,3,0,1] row_mask:0xf bank_mask:0xf
	v_mul_f32_e32 v208, v39, v208
	v_mul_f32_e32 v209, v39, v209
	v_mul_f32_e32 v210, v39, v210
	v_mul_f32_e32 v211, v39, v211
	v_mul_f32_e32 v212, v39, v212
	v_mul_f32_e32 v213, v39, v213
	v_mul_f32_e32 v214, v39, v214
	v_mul_f32_e32 v215, v39, v215
	v_mul_f32_e32 v208, v208, v104
	v_mul_f32_e32 v209, v209, v105
	v_mul_f32_e32 v210, v210, v106
	v_mul_f32_e32 v211, v211, v107
	v_mul_f32_e32 v212, v212, v108
	v_mul_f32_e32 v213, v213, v109
	v_mul_f32_e32 v214, v214, v110
	v_mul_f32_e32 v215, v215, v111
	v_fma_f32 v200, v200, v96, v208
	v_fma_f32 v201, v201, v97, v209
	v_fma_f32 v202, v202, v98, v210
	v_fma_f32 v203, v203, v99, v211
	v_fma_f32 v204, v204, v100, v212
	v_fma_f32 v205, v205, v101, v213
	v_fma_f32 v206, v206, v102, v214
	v_fma_f32 v207, v207, v103, v215
	v_cvt_pk_bf16_f32 v240, v200, v201
	v_cvt_pk_bf16_f32 v241, v202, v203
	v_cvt_pk_bf16_f32 v242, v204, v205
	v_cvt_pk_bf16_f32 v243, v206, v207
	v_add_u32_e32 v37, 0x24000, v37
	global_store_dwordx4 v37, v[240:243], s[0:1] offset:3072
	v_add_u32_e32 v34, 32, v34
	v_and_b32_e32 v35, 0xfff, v34
	v_lshrrev_b32_e32 v242, 6, v35
	v_and_b32_e32 v243, 63, v35
	v_cndmask_b32_e32 v242, v243, v242, vcc
	v_lshl_add_u32 v130, v242, 6, v38
	v_lshl_add_u64 v[244:245], s[8:9], 0, v[130:131]
	global_load_dwordx4 v[96:99], v[244:245], off
	global_load_dwordx4 v[100:103], v[244:245], off offset:16
	v_add_u32_e32 v130, 0x1000, v130
	v_lshl_add_u64 v[244:245], s[8:9], 0, v[130:131]
	global_load_dwordx4 v[104:107], v[244:245], off
	global_load_dwordx4 v[108:111], v[244:245], off offset:16
	s_waitcnt vmcnt(10)
	v_lshlrev_b32_e32 v200, 16, v68
	v_and_b32_e32 v201, 0xffff0000, v68
	v_lshlrev_b32_e32 v202, 16, v69
	v_and_b32_e32 v203, 0xffff0000, v69
	v_lshlrev_b32_e32 v204, 16, v70
	v_and_b32_e32 v205, 0xffff0000, v70
	v_lshlrev_b32_e32 v206, 16, v71
	v_and_b32_e32 v207, 0xffff0000, v71
	v_mul_f32_e32 v234, v200, v200
	v_fmac_f32_e32 v234, v201, v201
	v_fmac_f32_e32 v234, v202, v202
	v_fmac_f32_e32 v234, v203, v203
	v_fmac_f32_e32 v234, v204, v204
	v_fmac_f32_e32 v234, v205, v205
	v_fmac_f32_e32 v234, v206, v206
	v_fmac_f32_e32 v234, v207, v207
	s_nop 1
	v_add_f32_dpp v235, v234, v234 quad_perm:[1,0,3,2] row_mask:0xf bank_mask:0xf
	s_nop 1
	v_add_f32_dpp v234, v235, v235 quad_perm:[2,3,0,1] row_mask:0xf bank_mask:0xf
	s_nop 1
	v_add_f32_dpp v235, v234, v234 row_half_mirror row_mask:0xf bank_mask:0xf
	v_fmamk_f32 v235, v235, 0x3c800000, v217
	v_rsq_f32_e32 v235, v235
	s_nop 0
	v_mul_f32_e32 v200, v200, v235
	v_mul_f32_e32 v201, v201, v235
	v_mul_f32_e32 v202, v202, v235
	v_mul_f32_e32 v203, v203, v235
	v_mul_f32_e32 v204, v204, v235
	v_mul_f32_e32 v205, v205, v235
	v_mul_f32_e32 v206, v206, v235
	v_mul_f32_e32 v207, v207, v235
	v_mul_f32_e32 v200, v200, v40
	v_mul_f32_e32 v201, v201, v41
	v_mul_f32_e32 v202, v202, v42
	v_mul_f32_e32 v203, v203, v43
	v_mul_f32_e32 v204, v204, v44
	v_mul_f32_e32 v205, v205, v45
	v_mul_f32_e32 v206, v206, v46
	v_mul_f32_e32 v207, v207, v47
	s_nop 1
	v_mov_b32_dpp v208, v200 quad_perm:[2,3,0,1] row_mask:0xf bank_mask:0xf
	v_mov_b32_dpp v209, v201 quad_perm:[2,3,0,1] row_mask:0xf bank_mask:0xf
	v_mov_b32_dpp v210, v202 quad_perm:[2,3,0,1] row_mask:0xf bank_mask:0xf
	v_mov_b32_dpp v211, v203 quad_perm:[2,3,0,1] row_mask:0xf bank_mask:0xf
	v_mov_b32_dpp v212, v204 quad_perm:[2,3,0,1] row_mask:0xf bank_mask:0xf
	v_mov_b32_dpp v213, v205 quad_perm:[2,3,0,1] row_mask:0xf bank_mask:0xf
	v_mov_b32_dpp v214, v206 quad_perm:[2,3,0,1] row_mask:0xf bank_mask:0xf
	v_mov_b32_dpp v215, v207 quad_perm:[2,3,0,1] row_mask:0xf bank_mask:0xf
	v_mul_f32_e32 v208, v39, v208
	v_mul_f32_e32 v209, v39, v209
	v_mul_f32_e32 v210, v39, v210
	v_mul_f32_e32 v211, v39, v211
	v_mul_f32_e32 v212, v39, v212
	v_mul_f32_e32 v213, v39, v213
	v_mul_f32_e32 v214, v39, v214
	v_mul_f32_e32 v215, v39, v215
	v_mul_f32_e32 v208, v208, v122
	v_mul_f32_e32 v209, v209, v123
	v_mul_f32_e32 v210, v210, v124
	v_mul_f32_e32 v211, v211, v125
	v_mul_f32_e32 v212, v212, v126
	v_mul_f32_e32 v213, v213, v127
	v_mul_f32_e32 v214, v214, v128
	v_mul_f32_e32 v215, v215, v129
	v_fma_f32 v200, v200, v114, v208
	v_fma_f32 v201, v201, v115, v209
	v_fma_f32 v202, v202, v116, v210
	v_fma_f32 v203, v203, v117, v211
	v_fma_f32 v204, v204, v118, v212
	v_fma_f32 v205, v205, v119, v213
	v_fma_f32 v206, v206, v120, v214
	v_fma_f32 v207, v207, v121, v215
	v_cvt_pk_bf16_f32 v240, v200, v201
	v_cvt_pk_bf16_f32 v241, v202, v203
	v_cvt_pk_bf16_f32 v242, v204, v205
	v_cvt_pk_bf16_f32 v243, v206, v207
	v_add_u32_e32 v37, 0x24000, v37
	global_store_dwordx4 v37, v[240:243], s[0:1] offset:3072
	s_waitcnt vmcnt(6)
; __device__ __forceinline__ unsigned cvt_pk_bf16(float lo, float hi) { unsigned r; asm volatile("v_cvt_pk_bf16_f32 %0, %1, %2" : "=v"(r) : "v"(lo), "v"(hi)); return r; }
; __device__ __forceinline__ float bflo(unsigned w) { return __uint_as_float(w << 16); }
; __device__ __forceinline__ float bfhi(unsigned w) { return __uint_as_float(w & 0xffff0000u); }
;     __device__ __forceinline__ void post(int slot, int tid, const f32x4 (&r)[2]) const {
;         const f32x4 t = r[0] + r[1]; float s = (t[0] + t[1]) + (t[2] + t[3]);
;         s += __shfl_xor(s, 1);
;         if ((tid & 1) == 0) rst[slot * 256 + (tid >> 1)] = __builtin_amdgcn_rsqf(s * (1.0f / 1024.0f) + EPS);
;     }
; __device__ __forceinline__ void kprep_item(bf16_t* P, const float* kg, const float* rope, int idx, const u32x4 w) {
;     const int e8 = idx & 7, hk = (idx >> 3) & 1, row = idx >> 4;
;     float x[8] = {bflo(w.x), bfhi(w.x), bflo(w.y), bfhi(w.y), bflo(w.z), bfhi(w.z), bflo(w.w), bfhi(w.w)};
;     float ssq = 0.f;
; #pragma unroll
;     for (int e = 0; e < 8; ++e) ssq += x[e] * x[e];
;     ssq += __shfl_xor(ssq, 1); ssq += __shfl_xor(ssq, 2); ssq += __shfl_xor(ssq, 4);
;     const float rh = __builtin_amdgcn_rsqf(ssq * (1.0f / 64.0f) + EPS);
;     const int t = row & (SEQ - 1), ir = (e8 < 4) ? (t >> 6) : (t & 63), f0 = 8 * (e8 & 1);
;     const f32x4 g0 = *(const f32x4*)(kg + e8 * 8), g1 = *(const f32x4*)(kg + e8 * 8 + 4);
;     const f32x4 c0 = *(const f32x4*)(rope + ir * 16 + f0), c1 = *(const f32x4*)(rope + ir * 16 + f0 + 4);
;     const f32x4 s0 = *(const f32x4*)(rope + 1024 + ir * 16 + f0), s1 = *(const f32x4*)(rope + 1024 + ir * 16 + f0 + 4);
;     const float sgn = (e8 & 2) ? 1.0f : -1.0f;
;     float o[8];
; #pragma unroll
;     for (int e = 0; e < 8; ++e) {
;         const float y = x[e] * rh * (e < 4 ? g0[e & 3] : g1[e & 3]);
;         const float other = __shfl_xor(y, 2);
;         o[e] = y * (e < 4 ? c0[e & 3] : c1[e & 3]) + sgn * other * (e < 4 ? s0[e & 3] : s1[e & 3]);
;     }
;     u32x4 r; r.x = cvt_pk_bf16(o[0], o[1]); r.y = cvt_pk_bf16(o[2], o[3]); r.z = cvt_pk_bf16(o[4], o[5]); r.w = cvt_pk_bf16(o[6], o[7]);
;     *(u32x4*)(P + (size_t)row * EVEN_IN + 1536 + hk * 64 + e8 * 8) = r;
; }
	v_lshlrev_b32_e32 v200, 16, v72
	v_and_b32_e32 v201, 0xffff0000, v72
	v_lshlrev_b32_e32 v202, 16, v73
	v_and_b32_e32 v203, 0xffff0000, v73
	v_lshlrev_b32_e32 v204, 16, v74
	v_and_b32_e32 v205, 0xffff0000, v74
	v_lshlrev_b32_e32 v206, 16, v75
	v_and_b32_e32 v207, 0xffff0000, v75
	v_mul_f32_e32 v234, v200, v200
	v_fmac_f32_e32 v234, v201, v201
	v_fmac_f32_e32 v234, v202, v202
	v_fmac_f32_e32 v234, v203, v203
	v_fmac_f32_e32 v234, v204, v204
	v_fmac_f32_e32 v234, v205, v205
	v_fmac_f32_e32 v234, v206, v206
	v_fmac_f32_e32 v234, v207, v207
	s_nop 1
	v_add_f32_dpp v235, v234, v234 quad_perm:[1,0,3,2] row_mask:0xf bank_mask:0xf
	s_nop 1
	v_add_f32_dpp v234, v235, v235 quad_perm:[2,3,0,1] row_mask:0xf bank_mask:0xf
	s_nop 1
	v_add_f32_dpp v235, v234, v234 row_half_mirror row_mask:0xf bank_mask:0xf
	v_fmamk_f32 v235, v235, 0x3c800000, v217
	v_rsq_f32_e32 v235, v235
	s_nop 0
	v_mul_f32_e32 v200, v200, v235
	v_mul_f32_e32 v201, v201, v235
	v_mul_f32_e32 v202, v202, v235
	v_mul_f32_e32 v203, v203, v235
	v_mul_f32_e32 v204, v204, v235
	v_mul_f32_e32 v205, v205, v235
	v_mul_f32_e32 v206, v206, v235
	v_mul_f32_e32 v207, v207, v235
	v_mul_f32_e32 v200, v200, v40
	v_mul_f32_e32 v201, v201, v41
	v_mul_f32_e32 v202, v202, v42
	v_mul_f32_e32 v203, v203, v43
	v_mul_f32_e32 v204, v204, v44
	v_mul_f32_e32 v205, v205, v45
	v_mul_f32_e32 v206, v206, v46
	v_mul_f32_e32 v207, v207, v47
	s_nop 1
	v_mov_b32_dpp v208, v200 quad_perm:[2,3,0,1] row_mask:0xf bank_mask:0xf
	v_mov_b32_dpp v209, v201 quad_perm:[2,3,0,1] row_mask:0xf bank_mask:0xf
	v_mov_b32_dpp v210, v202 quad_perm:[2,3,0,1] row_mask:0xf bank_mask:0xf
	v_mov_b32_dpp v211, v203 quad_perm:[2,3,0,1] row_mask:0xf bank_mask:0xf
	v_mov_b32_dpp v212, v204 quad_perm:[2,3,0,1] row_mask:0xf bank_mask:0xf
	v_mov_b32_dpp v213, v205 quad_perm:[2,3,0,1] row_mask:0xf bank_mask:0xf
	v_mov_b32_dpp v214, v206 quad_perm:[2,3,0,1] row_mask:0xf bank_mask:0xf
	v_mov_b32_dpp v215, v207 quad_perm:[2,3,0,1] row_mask:0xf bank_mask:0xf
	v_mul_f32_e32 v208, v39, v208
	v_mul_f32_e32 v209, v39, v209
	v_mul_f32_e32 v210, v39, v210
	v_mul_f32_e32 v211, v39, v211
	v_mul_f32_e32 v212, v39, v212
	v_mul_f32_e32 v213, v39, v213
	v_mul_f32_e32 v214, v39, v214
	v_mul_f32_e32 v215, v39, v215
	v_mul_f32_e32 v208, v208, v88
	v_mul_f32_e32 v209, v209, v89
	v_mul_f32_e32 v210, v210, v90
	v_mul_f32_e32 v211, v211, v91
	v_mul_f32_e32 v212, v212, v92
	v_mul_f32_e32 v213, v213, v93
	v_mul_f32_e32 v214, v214, v94
	v_mul_f32_e32 v215, v215, v95
	v_fma_f32 v200, v200, v80, v208
	v_fma_f32 v201, v201, v81, v209
	v_fma_f32 v202, v202, v82, v210
	v_fma_f32 v203, v203, v83, v211
	v_fma_f32 v204, v204, v84, v212
	v_fma_f32 v205, v205, v85, v213
	v_fma_f32 v206, v206, v86, v214
	v_fma_f32 v207, v207, v87, v215
	v_cvt_pk_bf16_f32 v240, v200, v201
	v_cvt_pk_bf16_f32 v241, v202, v203
	v_cvt_pk_bf16_f32 v242, v204, v205
	v_cvt_pk_bf16_f32 v243, v206, v207
	v_add_u32_e32 v37, 0x24000, v37
	global_store_dwordx4 v37, v[240:243], s[0:1] offset:3072
	s_waitcnt vmcnt(2)
	v_lshlrev_b32_e32 v200, 16, v76
	v_and_b32_e32 v201, 0xffff0000, v76
	v_lshlrev_b32_e32 v202, 16, v77
	v_and_b32_e32 v203, 0xffff0000, v77
	v_lshlrev_b32_e32 v204, 16, v78
	v_and_b32_e32 v205, 0xffff0000, v78
	v_lshlrev_b32_e32 v206, 16, v79
	v_and_b32_e32 v207, 0xffff0000, v79
	v_mul_f32_e32 v234, v200, v200
	v_fmac_f32_e32 v234, v201, v201
	v_fmac_f32_e32 v234, v202, v202
	v_fmac_f32_e32 v234, v203, v203
	v_fmac_f32_e32 v234, v204, v204
	v_fmac_f32_e32 v234, v205, v205
	v_fmac_f32_e32 v234, v206, v206
	v_fmac_f32_e32 v234, v207, v207
	s_nop 1
	v_add_f32_dpp v235, v234, v234 quad_perm:[1,0,3,2] row_mask:0xf bank_mask:0xf
	s_nop 1
	v_add_f32_dpp v234, v235, v235 quad_perm:[2,3,0,1] row_mask:0xf bank_mask:0xf
	s_nop 1
	v_add_f32_dpp v235, v234, v234 row_half_mirror row_mask:0xf bank_mask:0xf
	v_fmamk_f32 v235, v235, 0x3c800000, v217
	v_rsq_f32_e32 v235, v235
	s_nop 0
	v_mul_f32_e32 v200, v200, v235
	v_mul_f32_e32 v201, v201, v235
	v_mul_f32_e32 v202, v202, v235
	v_mul_f32_e32 v203, v203, v235
	v_mul_f32_e32 v204, v204, v235
	v_mul_f32_e32 v205, v205, v235
	v_mul_f32_e32 v206, v206, v235
	v_mul_f32_e32 v207, v207, v235
	v_mul_f32_e32 v200, v200, v40
	v_mul_f32_e32 v201, v201, v41
	v_mul_f32_e32 v202, v202, v42
	v_mul_f32_e32 v203, v203, v43
	v_mul_f32_e32 v204, v204, v44
	v_mul_f32_e32 v205, v205, v45
	v_mul_f32_e32 v206, v206, v46
	v_mul_f32_e32 v207, v207, v47
	s_nop 1
	v_mov_b32_dpp v208, v200 quad_perm:[2,3,0,1] row_mask:0xf bank_mask:0xf
	v_mov_b32_dpp v209, v201 quad_perm:[2,3,0,1] row_mask:0xf bank_mask:0xf
	v_mov_b32_dpp v210, v202 quad_perm:[2,3,0,1] row_mask:0xf bank_mask:0xf
	v_mov_b32_dpp v211, v203 quad_perm:[2,3,0,1] row_mask:0xf bank_mask:0xf
	v_mov_b32_dpp v212, v204 quad_perm:[2,3,0,1] row_mask:0xf bank_mask:0xf
	v_mov_b32_dpp v213, v205 quad_perm:[2,3,0,1] row_mask:0xf bank_mask:0xf
	v_mov_b32_dpp v214, v206 quad_perm:[2,3,0,1] row_mask:0xf bank_mask:0xf
	v_mov_b32_dpp v215, v207 quad_perm:[2,3,0,1] row_mask:0xf bank_mask:0xf
	v_mul_f32_e32 v208, v39, v208
	v_mul_f32_e32 v209, v39, v209
	v_mul_f32_e32 v210, v39, v210
	v_mul_f32_e32 v211, v39, v211
	v_mul_f32_e32 v212, v39, v212
	v_mul_f32_e32 v213, v39, v213
	v_mul_f32_e32 v214, v39, v214
	v_mul_f32_e32 v215, v39, v215
	v_mul_f32_e32 v208, v208, v104
	v_mul_f32_e32 v209, v209, v105
	v_mul_f32_e32 v210, v210, v106
	v_mul_f32_e32 v211, v211, v107
	v_mul_f32_e32 v212, v212, v108
	v_mul_f32_e32 v213, v213, v109
	v_mul_f32_e32 v214, v214, v110
	v_mul_f32_e32 v215, v215, v111
	v_fma_f32 v200, v200, v96, v208
	v_fma_f32 v201, v201, v97, v209
	v_fma_f32 v202, v202, v98, v210
	v_fma_f32 v203, v203, v99, v211
	v_fma_f32 v204, v204, v100, v212
	v_fma_f32 v205, v205, v101, v213
	v_fma_f32 v206, v206, v102, v214
	v_fma_f32 v207, v207, v103, v215
	v_cvt_pk_bf16_f32 v240, v200, v201
	v_cvt_pk_bf16_f32 v241, v202, v203
	v_cvt_pk_bf16_f32 v242, v204, v205
	v_cvt_pk_bf16_f32 v243, v206, v207
	v_add_u32_e32 v37, 0x24000, v37
	global_store_dwordx4 v37, v[240:243], s[0:1] offset:3072
	v_readlane_b32 s13, v255, 49
	s_and_b64 vcc, exec, s[42:43]
.Lkp_skip:
	s_cbranch_vccnz .LBB0_352
	s_waitcnt vmcnt(0)
	v_pk_add_f32 v[8:9], v[2:3], v[6:7]
	v_pk_add_f32 v[10:11], v[0:1], v[4:5]
	v_add_f32_e32 v8, v8, v9
	v_add_f32_e32 v10, v10, v11
	v_add_f32_e32 v8, v10, v8
	ds_bpermute_b32 v9, v158, v8
	s_and_saveexec_b64 s[40:41], s[38:39]
	s_cbranch_execz .LBB0_364
	s_waitcnt lgkmcnt(0)
	v_add_f32_e32 v8, v8, v9
	v_fmamk_f32 v8, v8, 0x3a800000, v217
	v_rsq_f32_e32 v8, v8
	s_lshl_b32 s8, s57, 10
	s_and_b32 s8, s8, 0x400
	v_add_u32_e32 v9, s8, v162
	ds_write_b32 v9, v8
